# v17: v12 + accumulate-chain MFMA order in all 24 K-loop compute segments (loop bodies and peeled first iterations of the three GEMM copies; register dependences of time-shared blocks preserved)
# speedup vs baseline: 1.0067x; 1.0014x over previous
.LBB0_382:
	s_add_i32 s39, s33, 1
	s_mov_b32 s47, s37
	s_add_i32 s37, s39, s35
	s_mul_i32 s37, s37, s23
	s_add_i32 s37, s37, s22
	s_mov_b32 s43, s38
	s_add_i32 s38, s37, 0xffffff28
	s_cmpk_lt_i32 s38, 0x48
	s_cselect_b64 s[76:77], -1, 0
	s_cmpk_gt_i32 s38, 0x47
	s_cselect_b64 s[72:73], -1, 0
	s_cmp_lt_i32 s38, 36
	s_cselect_b32 s41, 0, 0xffffffdc
	s_cselect_b32 s44, 0, 4
	s_add_i32 s38, s41, s38
	s_and_b32 s45, s37, 3
	s_ashr_i32 s37, s38, 2
	s_or_b32 s38, s45, s44
	s_or_b32 s38, s38, s28
	s_and_b64 s[44:45], s[76:77], exec
	s_cselect_b32 s80, s38, s43
	s_cselect_b32 s44, s37, s47
	s_ashr_i32 s81, s80, 31
	s_lshl_b64 s[50:51], s[80:81], 19
	s_add_u32 s74, s9, s50
	s_addc_u32 s75, s18, s51
	s_ashr_i32 s45, s44, 31
	s_lshl_b64 s[44:45], s[44:45], 19
	s_add_u32 s78, s14, s44
	s_addc_u32 s79, s15, s45
	s_add_u32 s84, s66, 0x100
	s_addc_u32 s85, s67, 0
	v_add_u32_e32 v142, 0x10000, v140
	v_add_u32_e32 v143, 0x14000, v140
	s_add_u32 s82, s66, 0x180
	ds_read_b128 v[4:7], v142
	ds_read_b128 v[8:11], v142 offset:1024
	ds_read_b128 v[12:15], v142 offset:2048
	ds_read_b128 v[16:19], v142 offset:3072
	ds_read_b128 v[20:23], v143
	ds_read_b128 v[24:27], v143 offset:1024
	ds_read_b128 v[28:31], v143 offset:2048
	ds_read_b128 v[32:35], v143 offset:3072
	s_addc_u32 s83, s67, 0
	s_and_b64 s[44:45], s[76:77], exec
	s_cselect_b32 s43, s75, s67
	s_cselect_b32 s44, s74, s66
	s_add_u32 s50, s12, 0x100
	s_addc_u32 s51, s13, 0
	s_and_b64 s[52:53], s[76:77], exec
	s_mov_b32 s41, 2
	s_cselect_b32 s45, s79, s13
	s_cselect_b32 s47, s78, s12
	ds_read_b128 v[36:39], v141
	ds_read_b128 v[40:43], v141 offset:1024
	ds_read_b128 v[44:47], v141 offset:2048
	ds_read_b128 v[48:51], v141 offset:3072
	ds_read_b128 v[52:55], v141 offset:4096
	ds_read_b128 v[56:59], v141 offset:5120
	ds_read_b128 v[60:63], v141 offset:6144
	ds_read_b128 v[64:67], v141 offset:7168
	s_add_u32 s52, s66, 0x40080
	s_addc_u32 s53, s67, 0
	s_add_i32 m0, s16, 0xc000
	s_nop 0
	global_load_lds_dwordx4 v136, s[52:53]
	s_nop 0
	s_add_i32 m0, s16, 0xe000
	s_nop 0
	global_load_lds_dwordx4 v137, s[52:53]
	s_waitcnt vmcnt(8)
	s_waitcnt lgkmcnt(0)
	s_setprio 1
	s_barrier
	v_mfma_f32_16x16x32_bf16 v[68:71], v[4:7], v[36:39], 0
	v_mfma_f32_16x16x32_bf16 v[68:71], v[8:11], v[40:43], v[68:71]
	v_mfma_f32_16x16x32_bf16 v[72:75], v[12:15], v[36:39], 0
	v_mfma_f32_16x16x32_bf16 v[72:75], v[16:19], v[40:43], v[72:75]
	v_mfma_f32_16x16x32_bf16 v[76:79], v[4:7], v[44:47], 0
	v_mfma_f32_16x16x32_bf16 v[76:79], v[8:11], v[48:51], v[76:79]
	v_mfma_f32_16x16x32_bf16 v[80:83], v[12:15], v[44:47], 0
	v_mfma_f32_16x16x32_bf16 v[80:83], v[16:19], v[48:51], v[80:83]
	v_mfma_f32_16x16x32_bf16 v[84:87], v[4:7], v[52:55], 0
	v_mfma_f32_16x16x32_bf16 v[84:87], v[8:11], v[56:59], v[84:87]
	v_mfma_f32_16x16x32_bf16 v[88:91], v[12:15], v[52:55], 0
	v_mfma_f32_16x16x32_bf16 v[88:91], v[16:19], v[56:59], v[88:91]
	v_mfma_f32_16x16x32_bf16 v[92:95], v[4:7], v[60:63], 0
	v_mfma_f32_16x16x32_bf16 v[92:95], v[8:11], v[64:67], v[92:95]
	v_mfma_f32_16x16x32_bf16 v[96:99], v[12:15], v[60:63], 0
	v_mfma_f32_16x16x32_bf16 v[100:103], v[16:19], v[64:67], v[96:99]
	v_mfma_f32_16x16x32_bf16 v[96:99], v[20:23], v[36:39], 0
	v_mfma_f32_16x16x32_bf16 v[108:111], v[24:27], v[40:43], v[96:99]
	v_mfma_f32_16x16x32_bf16 v[36:39], v[28:31], v[36:39], 0
	v_mfma_f32_16x16x32_bf16 v[36:39], v[32:35], v[40:43], v[36:39]
	v_mfma_f32_16x16x32_bf16 v[40:43], v[20:23], v[44:47], 0
	v_mfma_f32_16x16x32_bf16 v[40:43], v[24:27], v[48:51], v[40:43]
	v_mfma_f32_16x16x32_bf16 v[44:47], v[28:31], v[44:47], 0
	v_mfma_f32_16x16x32_bf16 v[44:47], v[32:35], v[48:51], v[44:47]
	v_mfma_f32_16x16x32_bf16 v[48:51], v[20:23], v[52:55], 0
	v_mfma_f32_16x16x32_bf16 v[48:51], v[24:27], v[56:59], v[48:51]
	v_mfma_f32_16x16x32_bf16 v[52:55], v[28:31], v[52:55], 0
	v_mfma_f32_16x16x32_bf16 v[52:55], v[32:35], v[56:59], v[52:55]
	v_mfma_f32_16x16x32_bf16 v[56:59], v[20:23], v[60:63], 0
	v_mfma_f32_16x16x32_bf16 v[146:149], v[24:27], v[64:67], v[56:59]
	v_mfma_f32_16x16x32_bf16 v[56:59], v[28:31], v[60:63], 0
	v_mfma_f32_16x16x32_bf16 v[150:153], v[32:35], v[64:67], v[56:59]
	s_barrier
	s_setprio 0
	s_nop 4
	ds_read_b128 v[56:59], v141 offset:16384
	ds_read_b128 v[60:63], v141 offset:17408
	ds_read_b128 v[64:67], v141 offset:18432
	ds_read_b128 v[96:99], v141 offset:19456
	ds_read_b128 v[104:107], v141 offset:20480
	ds_read_b128 v[112:115], v141 offset:21504
	ds_read_b128 v[116:119], v141 offset:22528
	ds_read_b128 v[120:123], v141 offset:23552
	s_add_i32 m0, s16, 0x10000
	s_nop 0
	global_load_lds_dwordx4 v1, s[50:51]
	s_nop 0
	s_add_i32 m0, s16, 0x12000
	s_nop 0
	global_load_lds_dwordx4 v134, s[50:51]
	s_add_u32 s50, s12, 0x40100
	s_addc_u32 s51, s13, 0
	s_add_i32 m0, s16, 0x14000
	s_nop 0
	global_load_lds_dwordx4 v1, s[50:51]
	s_nop 0
	s_add_i32 m0, s16, 0x16000
	s_nop 0
	global_load_lds_dwordx4 v134, s[50:51]
	s_nop 0
	s_add_i32 m0, s16, 0
	s_nop 0
	global_load_lds_dwordx4 v136, s[84:85]
	s_nop 0
	s_add_i32 m0, s16, 0x2000
	s_nop 0
	global_load_lds_dwordx4 v137, s[84:85]
	s_waitcnt vmcnt(8)
	s_waitcnt lgkmcnt(0)
	s_setprio 1
	s_barrier
	v_mfma_f32_16x16x32_bf16 v[124:127], v[4:7], v[56:59], 0
	v_mfma_f32_16x16x32_bf16 v[154:157], v[8:11], v[60:63], v[124:127]
	v_mfma_f32_16x16x32_bf16 v[124:127], v[12:15], v[56:59], 0
	v_mfma_f32_16x16x32_bf16 v[158:161], v[16:19], v[60:63], v[124:127]
	v_mfma_f32_16x16x32_bf16 v[124:127], v[4:7], v[64:67], 0
	v_mfma_f32_16x16x32_bf16 v[162:165], v[8:11], v[96:99], v[124:127]
	v_mfma_f32_16x16x32_bf16 v[124:127], v[12:15], v[64:67], 0
	v_mfma_f32_16x16x32_bf16 v[166:169], v[16:19], v[96:99], v[124:127]
	v_mfma_f32_16x16x32_bf16 v[124:127], v[4:7], v[104:107], 0
	v_mfma_f32_16x16x32_bf16 v[172:175], v[8:11], v[112:115], v[124:127]
	v_mfma_f32_16x16x32_bf16 v[4:7], v[4:7], v[116:119], 0
	v_mfma_f32_16x16x32_bf16 v[4:7], v[8:11], v[120:123], v[4:7]
	v_mfma_f32_16x16x32_bf16 v[8:11], v[12:15], v[116:119], 0
	v_mfma_f32_16x16x32_bf16 v[8:11], v[16:19], v[120:123], v[8:11]
	v_mfma_f32_16x16x32_bf16 v[124:127], v[12:15], v[104:107], 0
	v_mfma_f32_16x16x32_bf16 v[176:179], v[16:19], v[112:115], v[124:127]
	v_mfma_f32_16x16x32_bf16 v[16:19], v[28:31], v[56:59], 0
	v_mfma_f32_16x16x32_bf16 v[180:183], v[32:35], v[60:63], v[16:19]
	v_mfma_f32_16x16x32_bf16 v[16:19], v[20:23], v[64:67], 0
	v_mfma_f32_16x16x32_bf16 v[184:187], v[24:27], v[96:99], v[16:19]
	v_mfma_f32_16x16x32_bf16 v[16:19], v[28:31], v[64:67], 0
	v_mfma_f32_16x16x32_bf16 v[188:191], v[32:35], v[96:99], v[16:19]
	v_mfma_f32_16x16x32_bf16 v[16:19], v[20:23], v[104:107], 0
	v_mfma_f32_16x16x32_bf16 v[196:199], v[24:27], v[112:115], v[16:19]
	v_mfma_f32_16x16x32_bf16 v[16:19], v[28:31], v[104:107], 0
	v_mfma_f32_16x16x32_bf16 v[200:203], v[32:35], v[112:115], v[16:19]
	v_mfma_f32_16x16x32_bf16 v[12:15], v[20:23], v[56:59], 0
	v_mfma_f32_16x16x32_bf16 v[12:15], v[24:27], v[60:63], v[12:15]
	v_mfma_f32_16x16x32_bf16 v[16:19], v[20:23], v[116:119], 0
	v_mfma_f32_16x16x32_bf16 v[204:207], v[24:27], v[120:123], v[16:19]
	v_mfma_f32_16x16x32_bf16 v[16:19], v[28:31], v[116:119], 0
	v_mfma_f32_16x16x32_bf16 v[208:211], v[32:35], v[120:123], v[16:19]
	s_barrier
	s_setprio 0
	v_add_u32_e32 v144, 0x18000, v140
	v_add_u32_e32 v145, 0x1c000, v140
	s_nop 2
	ds_read_b128 v[16:19], v144
	ds_read_b128 v[20:23], v144 offset:1024
	ds_read_b128 v[28:31], v144 offset:2048
	ds_read_b128 v[212:215], v144 offset:3072
	ds_read_b128 v[216:219], v145
	ds_read_b128 v[220:223], v145 offset:1024
	ds_read_b128 v[224:227], v145 offset:2048
	ds_read_b128 v[228:231], v145 offset:3072
	ds_read_b128 v[24:27], v141 offset:32768
	ds_read_b128 v[32:35], v141 offset:33792
	ds_read_b128 v[60:63], v141 offset:34816
	ds_read_b128 v[232:235], v141 offset:35840
	ds_read_b128 v[236:239], v141 offset:36864
	ds_read_b128 v[240:243], v141 offset:37888
	ds_read_b128 v[244:247], v141 offset:38912
	ds_read_b128 v[248:251], v141 offset:39936
	s_add_u32 s50, s66, 0x40100
	s_addc_u32 s51, s67, 0
	s_add_i32 m0, s16, 0x4000
	s_nop 0
	global_load_lds_dwordx4 v136, s[50:51]
	s_nop 0
	s_add_i32 m0, s16, 0x6000
	s_nop 0
	global_load_lds_dwordx4 v137, s[50:51]
	s_waitcnt vmcnt(8)
	s_waitcnt lgkmcnt(0)
	s_setprio 1
	s_barrier
	v_mfma_f32_16x16x32_bf16 v[56:59], v[16:19], v[24:27], v[68:71]
	v_mfma_f32_16x16x32_bf16 v[128:131], v[20:23], v[32:35], v[56:59]
	v_mfma_f32_16x16x32_bf16 v[56:59], v[28:31], v[24:27], v[72:75]
	v_mfma_f32_16x16x32_bf16 v[120:123], v[212:215], v[32:35], v[56:59]
	v_mfma_f32_16x16x32_bf16 v[56:59], v[16:19], v[60:63], v[76:79]
	v_mfma_f32_16x16x32_bf16 v[112:115], v[20:23], v[232:235], v[56:59]
	v_mfma_f32_16x16x32_bf16 v[56:59], v[28:31], v[60:63], v[80:83]
	v_mfma_f32_16x16x32_bf16 v[104:107], v[212:215], v[232:235], v[56:59]
	v_mfma_f32_16x16x32_bf16 v[56:59], v[16:19], v[236:239], v[84:87]
	v_mfma_f32_16x16x32_bf16 v[96:99], v[20:23], v[240:243], v[56:59]
	v_mfma_f32_16x16x32_bf16 v[56:59], v[28:31], v[236:239], v[88:91]
	v_mfma_f32_16x16x32_bf16 v[88:91], v[212:215], v[240:243], v[56:59]
	v_mfma_f32_16x16x32_bf16 v[56:59], v[16:19], v[244:247], v[92:95]
	v_mfma_f32_16x16x32_bf16 v[64:67], v[20:23], v[248:251], v[56:59]
	v_mfma_f32_16x16x32_bf16 v[56:59], v[28:31], v[244:247], v[100:103]
	v_mfma_f32_16x16x32_bf16 v[56:59], v[212:215], v[248:251], v[56:59]
	v_mfma_f32_16x16x32_bf16 v[68:71], v[216:219], v[24:27], v[108:111]
	v_mfma_f32_16x16x32_bf16 v[124:127], v[220:223], v[32:35], v[68:71]
	v_mfma_f32_16x16x32_bf16 v[24:27], v[224:227], v[24:27], v[36:39]
	v_mfma_f32_16x16x32_bf16 v[116:119], v[228:231], v[32:35], v[24:27]
	v_mfma_f32_16x16x32_bf16 v[24:27], v[216:219], v[60:63], v[40:43]
	v_mfma_f32_16x16x32_bf16 v[108:111], v[220:223], v[232:235], v[24:27]
	v_mfma_f32_16x16x32_bf16 v[24:27], v[224:227], v[60:63], v[44:47]
	v_mfma_f32_16x16x32_bf16 v[100:103], v[228:231], v[232:235], v[24:27]
	v_mfma_f32_16x16x32_bf16 v[24:27], v[216:219], v[236:239], v[48:51]
	v_mfma_f32_16x16x32_bf16 v[92:95], v[220:223], v[240:243], v[24:27]
	v_mfma_f32_16x16x32_bf16 v[24:27], v[224:227], v[236:239], v[52:55]
	v_mfma_f32_16x16x32_bf16 v[84:87], v[228:231], v[240:243], v[24:27]
	v_mfma_f32_16x16x32_bf16 v[24:27], v[216:219], v[244:247], v[146:149]
	v_mfma_f32_16x16x32_bf16 v[60:63], v[220:223], v[248:251], v[24:27]
	v_mfma_f32_16x16x32_bf16 v[24:27], v[224:227], v[244:247], v[150:153]
	v_mfma_f32_16x16x32_bf16 v[52:55], v[228:231], v[248:251], v[24:27]
	s_barrier
	s_setprio 0
	s_add_u32 s50, s12, 0x180
	ds_read_b128 v[36:39], v141 offset:49152
	ds_read_b128 v[44:47], v141 offset:50176
	ds_read_b128 v[146:149], v141 offset:51200
	ds_read_b128 v[150:153], v141 offset:52224
	ds_read_b128 v[232:235], v141 offset:53248
	ds_read_b128 v[236:239], v141 offset:54272
	ds_read_b128 v[240:243], v141 offset:55296
	ds_read_b128 v[244:247], v141 offset:56320
	s_addc_u32 s51, s13, 0
	s_add_i32 m0, s16, 0x18000
	s_nop 0
	global_load_lds_dwordx4 v1, s[50:51]
	s_nop 0
	s_add_i32 m0, s16, 0x1a000
	s_nop 0
	global_load_lds_dwordx4 v134, s[50:51]
	s_add_u32 s50, s12, 0x40180
	s_addc_u32 s51, s13, 0
	s_add_i32 m0, s16, 0x1c000
	s_nop 0
	global_load_lds_dwordx4 v1, s[50:51]
	s_nop 0
	s_add_i32 m0, s16, 0x1e000
	s_nop 0
	global_load_lds_dwordx4 v134, s[50:51]
	s_nop 0
	s_add_i32 m0, s16, 0x8000
	s_nop 0
	global_load_lds_dwordx4 v136, s[82:83]
	s_nop 0
	s_add_i32 m0, s16, 0xa000
	s_nop 0
	global_load_lds_dwordx4 v137, s[82:83]
	s_waitcnt vmcnt(8)
	s_waitcnt lgkmcnt(0)
	s_setprio 1
	s_barrier
	v_mfma_f32_16x16x32_bf16 v[24:27], v[16:19], v[36:39], v[154:157]
	v_mfma_f32_16x16x32_bf16 v[80:83], v[20:23], v[44:47], v[24:27]
	v_mfma_f32_16x16x32_bf16 v[24:27], v[28:31], v[36:39], v[158:161]
	v_mfma_f32_16x16x32_bf16 v[72:75], v[212:215], v[44:47], v[24:27]
	v_mfma_f32_16x16x32_bf16 v[24:27], v[16:19], v[146:149], v[162:165]
	v_mfma_f32_16x16x32_bf16 v[48:51], v[20:23], v[150:153], v[24:27]
	v_mfma_f32_16x16x32_bf16 v[24:27], v[28:31], v[146:149], v[166:169]
	v_mfma_f32_16x16x32_bf16 v[40:43], v[212:215], v[150:153], v[24:27]
	v_mfma_f32_16x16x32_bf16 v[24:27], v[16:19], v[232:235], v[172:175]
	v_mfma_f32_16x16x32_bf16 v[32:35], v[20:23], v[236:239], v[24:27]
	v_mfma_f32_16x16x32_bf16 v[4:7], v[16:19], v[240:243], v[4:7]
	v_mfma_f32_16x16x32_bf16 v[16:19], v[20:23], v[244:247], v[4:7]
	v_mfma_f32_16x16x32_bf16 v[24:27], v[28:31], v[232:235], v[176:179]
	v_mfma_f32_16x16x32_bf16 v[24:27], v[212:215], v[236:239], v[24:27]
	v_mfma_f32_16x16x32_bf16 v[4:7], v[28:31], v[240:243], v[8:11]
	v_mfma_f32_16x16x32_bf16 v[8:11], v[212:215], v[244:247], v[4:7]
	v_mfma_f32_16x16x32_bf16 v[4:7], v[216:219], v[36:39], v[12:15]
	v_mfma_f32_16x16x32_bf16 v[76:79], v[220:223], v[44:47], v[4:7]
	v_mfma_f32_16x16x32_bf16 v[4:7], v[224:227], v[36:39], v[180:183]
	v_mfma_f32_16x16x32_bf16 v[68:71], v[228:231], v[44:47], v[4:7]
	v_mfma_f32_16x16x32_bf16 v[4:7], v[216:219], v[146:149], v[184:187]
	v_mfma_f32_16x16x32_bf16 v[44:47], v[220:223], v[150:153], v[4:7]
	v_mfma_f32_16x16x32_bf16 v[4:7], v[224:227], v[146:149], v[188:191]
	v_mfma_f32_16x16x32_bf16 v[36:39], v[228:231], v[150:153], v[4:7]
	v_mfma_f32_16x16x32_bf16 v[4:7], v[216:219], v[232:235], v[196:199]
	v_mfma_f32_16x16x32_bf16 v[28:31], v[220:223], v[236:239], v[4:7]
	v_mfma_f32_16x16x32_bf16 v[4:7], v[224:227], v[232:235], v[200:203]
	v_mfma_f32_16x16x32_bf16 v[20:23], v[228:231], v[236:239], v[4:7]
	v_mfma_f32_16x16x32_bf16 v[4:7], v[216:219], v[240:243], v[204:207]
	v_mfma_f32_16x16x32_bf16 v[12:15], v[220:223], v[244:247], v[4:7]
	v_mfma_f32_16x16x32_bf16 v[4:7], v[224:227], v[240:243], v[208:211]
	v_mfma_f32_16x16x32_bf16 v[4:7], v[228:231], v[244:247], v[4:7]
	s_barrier
	s_setprio 0
	s_lshl_b32 s50, s80, 6
	s_addk_i32 s50, 0x4000
	s_lshl_b64 s[52:53], s[80:81], 14
	s_add_u32 s82, s6, s52
	s_addc_u32 s83, s7, s53
	s_lshl_b32 s51, s80, 8
	s_and_b32 s51, s51, 0x400
	s_add_i32 s51, s51, 0
	s_add_i32 s51, s51, 0x24400

.LBB0_728:
	v_add_u32_e32 v137, 0x10000, v2
	v_add_u32_e32 v138, 0x14000, v2
	s_and_b64 s[2:3], exec, s[84:85]
	ds_read_b128 v[4:7], v137
	ds_read_b128 v[8:11], v137 offset:1024
	ds_read_b128 v[12:15], v137 offset:2048
	ds_read_b128 v[16:19], v137 offset:3072
	ds_read_b128 v[20:23], v138
	ds_read_b128 v[24:27], v138 offset:1024
	ds_read_b128 v[28:31], v138 offset:2048
	ds_read_b128 v[32:35], v138 offset:3072
	s_cselect_b32 s47, s6, s29
	s_add_u32 s12, s78, 0x100
	s_addc_u32 s13, s79, 0
	s_add_u32 s2, s78, 0x180
	s_addc_u32 s3, s79, 0
	s_add_u32 s6, s76, 0x100
	s_addc_u32 s7, s77, 0
	ds_read_b128 v[36:39], v136
	ds_read_b128 v[40:43], v136 offset:1024
	ds_read_b128 v[44:47], v136 offset:2048
	ds_read_b128 v[48:51], v136 offset:3072
	ds_read_b128 v[52:55], v136 offset:4096
	ds_read_b128 v[56:59], v136 offset:5120
	ds_read_b128 v[60:63], v136 offset:6144
	ds_read_b128 v[64:67], v136 offset:7168
	s_add_u32 s59, s78, s16
	s_addc_u32 s38, s79, 0
	s_add_u32 s26, s59, 0x80
	s_addc_u32 s27, s38, 0
	s_add_i32 m0, s43, 0xc000
	s_nop 0
	global_load_lds_dwordx4 v134, s[26:27]
	s_nop 0
	s_add_i32 m0, s43, 0xe000
	s_nop 0
	global_load_lds_dwordx4 v135, s[26:27]
	s_waitcnt vmcnt(8)
	s_waitcnt lgkmcnt(0)
	s_setprio 1
	s_barrier
	v_mfma_f32_16x16x32_bf16 v[86:89], v[4:7], v[52:55], 0
	v_mfma_f32_16x16x32_bf16 v[94:97], v[8:11], v[56:59], v[86:89]
	v_mfma_f32_16x16x32_bf16 v[86:89], v[12:15], v[52:55], 0
	v_mfma_f32_16x16x32_bf16 v[98:101], v[16:19], v[56:59], v[86:89]
	v_mfma_f32_16x16x32_bf16 v[86:89], v[4:7], v[60:63], 0
	v_mfma_f32_16x16x32_bf16 v[102:105], v[8:11], v[64:67], v[86:89]
	v_mfma_f32_16x16x32_bf16 v[68:71], v[4:7], v[36:39], 0
	v_mfma_f32_16x16x32_bf16 v[68:71], v[8:11], v[40:43], v[68:71]
	v_mfma_f32_16x16x32_bf16 v[72:75], v[12:15], v[36:39], 0
	v_mfma_f32_16x16x32_bf16 v[74:77], v[16:19], v[40:43], v[72:75]
	v_mfma_f32_16x16x32_bf16 v[78:81], v[4:7], v[44:47], 0
	v_mfma_f32_16x16x32_bf16 v[78:81], v[8:11], v[48:51], v[78:81]
	v_mfma_f32_16x16x32_bf16 v[82:85], v[12:15], v[44:47], 0
	v_mfma_f32_16x16x32_bf16 v[82:85], v[16:19], v[48:51], v[82:85]
	v_mfma_f32_16x16x32_bf16 v[86:89], v[12:15], v[60:63], 0
	v_mfma_f32_16x16x32_bf16 v[106:109], v[16:19], v[64:67], v[86:89]
	v_mfma_f32_16x16x32_bf16 v[86:89], v[20:23], v[36:39], 0
	v_mfma_f32_16x16x32_bf16 v[110:113], v[24:27], v[40:43], v[86:89]
	v_mfma_f32_16x16x32_bf16 v[36:39], v[28:31], v[36:39], 0
	v_mfma_f32_16x16x32_bf16 v[36:39], v[32:35], v[40:43], v[36:39]
	v_mfma_f32_16x16x32_bf16 v[40:43], v[20:23], v[44:47], 0
	v_mfma_f32_16x16x32_bf16 v[40:43], v[24:27], v[48:51], v[40:43]
	v_mfma_f32_16x16x32_bf16 v[44:47], v[28:31], v[44:47], 0
	v_mfma_f32_16x16x32_bf16 v[44:47], v[32:35], v[48:51], v[44:47]
	v_mfma_f32_16x16x32_bf16 v[48:51], v[20:23], v[52:55], 0
	v_mfma_f32_16x16x32_bf16 v[48:51], v[24:27], v[56:59], v[48:51]
	v_mfma_f32_16x16x32_bf16 v[52:55], v[28:31], v[52:55], 0
	v_mfma_f32_16x16x32_bf16 v[52:55], v[32:35], v[56:59], v[52:55]
	v_mfma_f32_16x16x32_bf16 v[56:59], v[20:23], v[60:63], 0
	v_mfma_f32_16x16x32_bf16 v[56:59], v[24:27], v[64:67], v[56:59]
	v_mfma_f32_16x16x32_bf16 v[60:63], v[28:31], v[60:63], 0
	v_mfma_f32_16x16x32_bf16 v[60:63], v[32:35], v[64:67], v[60:63]
	s_barrier
	s_setprio 0
	ds_read_b128 v[64:67], v136 offset:16384
	ds_read_b128 v[86:89], v136 offset:17408
	ds_read_b128 v[90:93], v136 offset:18432
	ds_read_b128 v[114:117], v136 offset:19456
	ds_read_b128 v[118:121], v136 offset:20480
	ds_read_b128 v[122:125], v136 offset:21504
	ds_read_b128 v[126:129], v136 offset:22528
	ds_read_b128 v[130:133], v136 offset:23552
	s_add_i32 m0, s43, 0x10000
	s_nop 0
	global_load_lds_dwordx4 v134, s[6:7]
	s_nop 0
	s_add_i32 m0, s43, 0x12000
	s_nop 0
	global_load_lds_dwordx4 v135, s[6:7]
	s_add_u32 s6, s6, s16
	s_addc_u32 s7, s7, 0
	s_add_i32 m0, s43, 0x14000
	s_nop 0
	global_load_lds_dwordx4 v134, s[6:7]
	s_nop 0
	s_add_i32 m0, s43, 0x16000
	s_nop 0
	global_load_lds_dwordx4 v135, s[6:7]
	s_nop 0
	s_add_i32 m0, s43, 0
	s_nop 0
	global_load_lds_dwordx4 v134, s[12:13]
	s_nop 0
	s_add_i32 m0, s43, 0x2000
	s_nop 0
	global_load_lds_dwordx4 v135, s[12:13]
	s_waitcnt vmcnt(8)
	s_waitcnt lgkmcnt(0)
	s_setprio 1
	s_barrier
	v_mfma_f32_16x16x32_bf16 v[140:143], v[4:7], v[64:67], 0
	v_mfma_f32_16x16x32_bf16 v[142:145], v[8:11], v[86:89], v[140:143]
	v_mfma_f32_16x16x32_bf16 v[150:153], v[4:7], v[90:93], 0
	v_mfma_f32_16x16x32_bf16 v[150:153], v[8:11], v[114:117], v[150:153]
	v_mfma_f32_16x16x32_bf16 v[158:161], v[4:7], v[118:121], 0
	v_mfma_f32_16x16x32_bf16 v[158:161], v[8:11], v[122:125], v[158:161]
	v_mfma_f32_16x16x32_bf16 v[4:7], v[4:7], v[126:129], 0
	v_mfma_f32_16x16x32_bf16 v[166:169], v[8:11], v[130:133], v[4:7]
	v_mfma_f32_16x16x32_bf16 v[146:149], v[12:15], v[64:67], 0
	v_mfma_f32_16x16x32_bf16 v[146:149], v[16:19], v[86:89], v[146:149]
	v_mfma_f32_16x16x32_bf16 v[154:157], v[12:15], v[90:93], 0
	v_mfma_f32_16x16x32_bf16 v[154:157], v[16:19], v[114:117], v[154:157]
	v_mfma_f32_16x16x32_bf16 v[162:165], v[12:15], v[118:121], 0
	v_mfma_f32_16x16x32_bf16 v[162:165], v[16:19], v[122:125], v[162:165]
	v_mfma_f32_16x16x32_bf16 v[4:7], v[12:15], v[126:129], 0
	v_mfma_f32_16x16x32_bf16 v[172:175], v[16:19], v[130:133], v[4:7]
	v_mfma_f32_16x16x32_bf16 v[4:7], v[20:23], v[64:67], 0
	v_mfma_f32_16x16x32_bf16 v[176:179], v[24:27], v[86:89], v[4:7]
	v_mfma_f32_16x16x32_bf16 v[4:7], v[28:31], v[64:67], 0
	v_mfma_f32_16x16x32_bf16 v[64:67], v[32:35], v[86:89], v[4:7]
	v_mfma_f32_16x16x32_bf16 v[4:7], v[20:23], v[90:93], 0
	v_mfma_f32_16x16x32_bf16 v[180:183], v[24:27], v[114:117], v[4:7]
	v_mfma_f32_16x16x32_bf16 v[4:7], v[28:31], v[90:93], 0
	v_mfma_f32_16x16x32_bf16 v[184:187], v[32:35], v[114:117], v[4:7]
	v_mfma_f32_16x16x32_bf16 v[4:7], v[20:23], v[118:121], 0
	v_mfma_f32_16x16x32_bf16 v[196:199], v[24:27], v[122:125], v[4:7]
	v_mfma_f32_16x16x32_bf16 v[4:7], v[28:31], v[118:121], 0
	v_mfma_f32_16x16x32_bf16 v[200:203], v[32:35], v[122:125], v[4:7]
	v_mfma_f32_16x16x32_bf16 v[4:7], v[20:23], v[126:129], 0
	v_mfma_f32_16x16x32_bf16 v[204:207], v[24:27], v[130:133], v[4:7]
	v_mfma_f32_16x16x32_bf16 v[4:7], v[28:31], v[126:129], 0
	v_mfma_f32_16x16x32_bf16 v[208:211], v[32:35], v[130:133], v[4:7]
	s_barrier
	s_setprio 0
	v_add_u32_e32 v139, 0x18000, v2
	v_add_u32_e32 v140, 0x1c000, v2
	ds_read_b128 v[18:21], v139
	ds_read_b128 v[212:215], v139 offset:1024
	ds_read_b128 v[216:219], v139 offset:2048
	ds_read_b128 v[220:223], v139 offset:3072
	ds_read_b128 v[224:227], v140
	ds_read_b128 v[228:231], v140 offset:1024
	ds_read_b128 v[232:235], v140 offset:2048
	ds_read_b128 v[236:239], v140 offset:3072
	ds_read_b128 v[4:7], v136 offset:32768
	ds_read_b128 v[8:11], v136 offset:33792
	ds_read_b128 v[12:15], v136 offset:34816
	ds_read_b128 v[22:25], v136 offset:35840
	ds_read_b128 v[26:29], v136 offset:36864
	ds_read_b128 v[30:33], v136 offset:37888
	ds_read_b128 v[130:133], v136 offset:38912
	ds_read_b128 v[240:243], v136 offset:39936
	s_add_u32 s6, s12, s16
	s_addc_u32 s7, s13, 0
	s_add_i32 m0, s43, 0x4000
	s_nop 0
	global_load_lds_dwordx4 v134, s[6:7]
	s_nop 0
	s_add_i32 m0, s43, 0x6000
	s_nop 0
	global_load_lds_dwordx4 v135, s[6:7]
	s_waitcnt vmcnt(8)
	s_waitcnt lgkmcnt(0)
	s_setprio 1
	s_barrier
	v_mfma_f32_16x16x32_bf16 v[74:77], v[216:219], v[4:7], v[74:77]
	v_mfma_f32_16x16x32_bf16 v[86:89], v[220:223], v[8:11], v[74:77]
	v_mfma_f32_16x16x32_bf16 v[74:77], v[18:21], v[12:15], v[78:81]
	v_mfma_f32_16x16x32_bf16 v[74:77], v[212:215], v[22:25], v[74:77]
	v_mfma_f32_16x16x32_bf16 v[78:81], v[216:219], v[12:15], v[82:85]
	v_mfma_f32_16x16x32_bf16 v[90:93], v[220:223], v[22:25], v[78:81]
	v_mfma_f32_16x16x32_bf16 v[82:85], v[216:219], v[26:29], v[98:101]
	v_mfma_f32_16x16x32_bf16 v[68:71], v[18:21], v[4:7], v[68:71]
	v_mfma_f32_16x16x32_bf16 v[70:73], v[212:215], v[8:11], v[68:71]
	v_mfma_f32_16x16x32_bf16 v[78:81], v[18:21], v[26:29], v[94:97]
	v_mfma_f32_16x16x32_bf16 v[78:81], v[212:215], v[30:33], v[78:81]
	v_mfma_f32_16x16x32_bf16 v[94:97], v[220:223], v[30:33], v[82:85]
	v_mfma_f32_16x16x32_bf16 v[82:85], v[18:21], v[130:133], v[102:105]
	v_mfma_f32_16x16x32_bf16 v[82:85], v[212:215], v[240:243], v[82:85]
	v_mfma_f32_16x16x32_bf16 v[98:101], v[216:219], v[130:133], v[106:109]
	v_mfma_f32_16x16x32_bf16 v[98:101], v[220:223], v[240:243], v[98:101]
	v_mfma_f32_16x16x32_bf16 v[102:105], v[224:227], v[4:7], v[110:113]
	v_mfma_f32_16x16x32_bf16 v[102:105], v[228:231], v[8:11], v[102:105]
	v_mfma_f32_16x16x32_bf16 v[4:7], v[232:235], v[4:7], v[36:39]
	v_mfma_f32_16x16x32_bf16 v[118:121], v[236:239], v[8:11], v[4:7]
	v_mfma_f32_16x16x32_bf16 v[4:7], v[224:227], v[12:15], v[40:43]
	v_mfma_f32_16x16x32_bf16 v[106:109], v[228:231], v[22:25], v[4:7]
	v_mfma_f32_16x16x32_bf16 v[4:7], v[232:235], v[12:15], v[44:47]
	v_mfma_f32_16x16x32_bf16 v[122:125], v[236:239], v[22:25], v[4:7]
	v_mfma_f32_16x16x32_bf16 v[4:7], v[224:227], v[26:29], v[48:51]
	v_mfma_f32_16x16x32_bf16 v[110:113], v[228:231], v[30:33], v[4:7]
	v_mfma_f32_16x16x32_bf16 v[4:7], v[232:235], v[26:29], v[52:55]
	v_mfma_f32_16x16x32_bf16 v[126:129], v[236:239], v[30:33], v[4:7]
	v_mfma_f32_16x16x32_bf16 v[4:7], v[224:227], v[130:133], v[56:59]
	v_mfma_f32_16x16x32_bf16 v[114:117], v[228:231], v[240:243], v[4:7]
	v_mfma_f32_16x16x32_bf16 v[4:7], v[232:235], v[130:133], v[60:63]
	v_mfma_f32_16x16x32_bf16 v[130:133], v[236:239], v[240:243], v[4:7]
	s_barrier
	s_setprio 0
	s_add_u32 s6, s76, 0x180
	ds_read_b128 v[42:45], v136 offset:49152
	ds_read_b128 v[46:49], v136 offset:50176
	ds_read_b128 v[50:53], v136 offset:51200
	ds_read_b128 v[58:61], v136 offset:52224
	ds_read_b128 v[240:243], v136 offset:53248
	ds_read_b128 v[244:247], v136 offset:54272
	ds_read_b128 v[248:251], v136 offset:55296
	ds_read_b128 v[188:191], v136 offset:56320
	s_addc_u32 s7, s77, 0
	s_add_i32 m0, s43, 0x18000
	s_nop 0
	global_load_lds_dwordx4 v134, s[6:7]
	s_nop 0
	s_add_i32 m0, s43, 0x1a000
	s_nop 0
	global_load_lds_dwordx4 v135, s[6:7]
	s_add_u32 s6, s6, s16
	s_addc_u32 s7, s7, 0
	s_add_i32 m0, s43, 0x1c000
	s_nop 0
	global_load_lds_dwordx4 v134, s[6:7]
	s_nop 0
	s_add_i32 m0, s43, 0x1e000
	s_nop 0
	global_load_lds_dwordx4 v135, s[6:7]
	s_nop 0
	s_add_i32 m0, s43, 0x8000
	s_nop 0
	global_load_lds_dwordx4 v134, s[2:3]
	s_nop 0
	s_add_i32 m0, s43, 0xa000
	s_nop 0
	global_load_lds_dwordx4 v135, s[2:3]
	s_waitcnt vmcnt(8)
	s_waitcnt lgkmcnt(0)
	s_setprio 1
	s_barrier
	v_mfma_f32_16x16x32_bf16 v[10:13], v[216:219], v[42:45], v[146:149]
	v_mfma_f32_16x16x32_bf16 v[22:25], v[220:223], v[46:49], v[10:13]
	v_mfma_f32_16x16x32_bf16 v[14:17], v[216:219], v[50:53], v[154:157]
	v_mfma_f32_16x16x32_bf16 v[26:29], v[220:223], v[58:61], v[14:17]
	v_mfma_f32_16x16x32_bf16 v[4:7], v[18:21], v[42:45], v[142:145]
	v_mfma_f32_16x16x32_bf16 v[6:9], v[212:215], v[46:49], v[4:7]
	v_mfma_f32_16x16x32_bf16 v[10:13], v[18:21], v[50:53], v[150:153]
	v_mfma_f32_16x16x32_bf16 v[10:13], v[212:215], v[58:61], v[10:13]
	v_mfma_f32_16x16x32_bf16 v[14:17], v[18:21], v[240:243], v[158:161]
	v_mfma_f32_16x16x32_bf16 v[14:17], v[212:215], v[244:247], v[14:17]
	v_mfma_f32_16x16x32_bf16 v[30:33], v[216:219], v[240:243], v[162:165]
	v_mfma_f32_16x16x32_bf16 v[30:33], v[220:223], v[244:247], v[30:33]
	v_mfma_f32_16x16x32_bf16 v[18:21], v[18:21], v[248:251], v[166:169]
	v_mfma_f32_16x16x32_bf16 v[18:21], v[212:215], v[188:191], v[18:21]
	v_mfma_f32_16x16x32_bf16 v[34:37], v[216:219], v[248:251], v[172:175]
	v_mfma_f32_16x16x32_bf16 v[34:37], v[220:223], v[188:191], v[34:37]
	v_mfma_f32_16x16x32_bf16 v[38:41], v[224:227], v[42:45], v[176:179]
	v_mfma_f32_16x16x32_bf16 v[38:41], v[228:231], v[46:49], v[38:41]
	v_mfma_f32_16x16x32_bf16 v[42:45], v[232:235], v[42:45], v[64:67]
	v_mfma_f32_16x16x32_bf16 v[54:57], v[236:239], v[46:49], v[42:45]
	v_mfma_f32_16x16x32_bf16 v[42:45], v[224:227], v[50:53], v[180:183]
	v_mfma_f32_16x16x32_bf16 v[42:45], v[228:231], v[58:61], v[42:45]
	v_mfma_f32_16x16x32_bf16 v[46:49], v[232:235], v[50:53], v[184:187]
	v_mfma_f32_16x16x32_bf16 v[58:61], v[236:239], v[58:61], v[46:49]
	v_mfma_f32_16x16x32_bf16 v[50:53], v[232:235], v[240:243], v[200:203]
	v_mfma_f32_16x16x32_bf16 v[62:65], v[236:239], v[244:247], v[50:53]
	v_mfma_f32_16x16x32_bf16 v[46:49], v[224:227], v[240:243], v[196:199]
	v_mfma_f32_16x16x32_bf16 v[46:49], v[228:231], v[244:247], v[46:49]
	v_mfma_f32_16x16x32_bf16 v[50:53], v[224:227], v[248:251], v[204:207]
	v_mfma_f32_16x16x32_bf16 v[50:53], v[228:231], v[188:191], v[50:53]
	v_mfma_f32_16x16x32_bf16 v[66:69], v[232:235], v[248:251], v[208:211]
	v_mfma_f32_16x16x32_bf16 v[66:69], v[236:239], v[188:191], v[66:69]
	s_barrier
	s_setprio 0
	s_add_i32 s2, s47, 1
	s_lshl_b32 s72, s47, 6
	s_and_b32 s3, s2, 31
	s_lshl_b32 s2, s2, 6
	s_add_i32 s6, s72, 0x9000
	s_add_i32 s7, s72, 0x8000
	s_add_i32 s18, s72, 0x7000
	s_addk_i32 s2, 0x6000
	s_cmp_eq_u32 s3, 0
	s_cselect_b32 s26, 0, 32
	s_cselect_b32 s27, 0, s2
	s_add_i32 s40, s72, 0x6000
	s_add_i32 s41, s72, 0x5000
	s_and_b32 s2, s47, 31
	s_add_i32 s3, s72, 0x4fc0
	s_cmp_eq_u32 s2, 0
	s_cselect_b32 s50, 0, 0x48
	s_cselect_b32 s52, 0, s3
	s_add_i32 s58, s72, 0x4000
	s_addk_i32 s72, 0x3000
	s_mov_b32 s90, 2
	s_branch .LBB0_731

.LBB0_730:
	s_or_b32 s20, s90, 1
	s_add_i32 s90, s90, 2
	s_mov_b32 s91, s21
	ds_read_b128 v[142:145], v137
	ds_read_b128 v[146:149], v137 offset:1024
	ds_read_b128 v[150:153], v137 offset:2048
	ds_read_b128 v[154:157], v137 offset:3072
	ds_read_b128 v[158:161], v138
	ds_read_b128 v[162:165], v138 offset:1024
	ds_read_b128 v[166:169], v138 offset:2048
	ds_read_b128 v[172:175], v138 offset:3072
	s_lshl_b64 s[96:97], s[20:21], 7
	s_lshl_b64 s[2:3], s[90:91], 7
	s_add_u32 s20, s78, s2
	s_addc_u32 s73, s79, s3
	s_and_b64 s[12:13], s[92:93], exec
	s_cselect_b32 s95, s73, s87
	s_cselect_b32 s94, s20, s86
	s_add_u32 s12, s76, s2
	s_addc_u32 s13, s77, s3
	s_and_b64 s[2:3], s[92:93], exec
	s_cselect_b32 s93, s13, s89
	s_cselect_b32 s92, s12, s88
	s_add_u32 s2, s94, 0x80
	s_addc_u32 s3, s95, 0
	s_add_u32 s12, s92, 0x80
	s_addc_u32 s13, s93, 0
	ds_read_b128 v[176:179], v136
	ds_read_b128 v[180:183], v136 offset:1024
	ds_read_b128 v[184:187], v136 offset:2048
	ds_read_b128 v[188:191], v136 offset:3072
	ds_read_b128 v[196:199], v136 offset:4096
	ds_read_b128 v[200:203], v136 offset:5120
	ds_read_b128 v[204:207], v136 offset:6144
	ds_read_b128 v[208:211], v136 offset:7168
	s_add_u32 s96, s59, s96
	s_addc_u32 s97, s38, s97
	s_add_i32 m0, s43, 0xc000
	s_nop 0
	global_load_lds_dwordx4 v134, s[96:97]
	s_nop 0
	s_add_i32 m0, s43, 0xe000
	s_nop 0
	global_load_lds_dwordx4 v135, s[96:97]
	s_waitcnt vmcnt(8)
	s_waitcnt lgkmcnt(0)
	s_setprio 1
	s_barrier
	v_mfma_f32_16x16x32_bf16 v[70:73], v[142:145], v[176:179], v[70:73]
	v_mfma_f32_16x16x32_bf16 v[70:73], v[146:149], v[180:183], v[70:73]
	v_mfma_f32_16x16x32_bf16 v[86:89], v[150:153], v[176:179], v[86:89]
	v_mfma_f32_16x16x32_bf16 v[86:89], v[154:157], v[180:183], v[86:89]
	v_mfma_f32_16x16x32_bf16 v[74:77], v[142:145], v[184:187], v[74:77]
	v_mfma_f32_16x16x32_bf16 v[74:77], v[146:149], v[188:191], v[74:77]
	v_mfma_f32_16x16x32_bf16 v[90:93], v[150:153], v[184:187], v[90:93]
	v_mfma_f32_16x16x32_bf16 v[90:93], v[154:157], v[188:191], v[90:93]
	v_mfma_f32_16x16x32_bf16 v[78:81], v[142:145], v[196:199], v[78:81]
	v_mfma_f32_16x16x32_bf16 v[78:81], v[146:149], v[200:203], v[78:81]
	v_mfma_f32_16x16x32_bf16 v[94:97], v[150:153], v[196:199], v[94:97]
	v_mfma_f32_16x16x32_bf16 v[94:97], v[154:157], v[200:203], v[94:97]
	v_mfma_f32_16x16x32_bf16 v[82:85], v[142:145], v[204:207], v[82:85]
	v_mfma_f32_16x16x32_bf16 v[82:85], v[146:149], v[208:211], v[82:85]
	v_mfma_f32_16x16x32_bf16 v[98:101], v[150:153], v[204:207], v[98:101]
	v_mfma_f32_16x16x32_bf16 v[98:101], v[154:157], v[208:211], v[98:101]
	v_mfma_f32_16x16x32_bf16 v[102:105], v[158:161], v[176:179], v[102:105]
	v_mfma_f32_16x16x32_bf16 v[102:105], v[162:165], v[180:183], v[102:105]
	v_mfma_f32_16x16x32_bf16 v[118:121], v[166:169], v[176:179], v[118:121]
	v_mfma_f32_16x16x32_bf16 v[118:121], v[172:175], v[180:183], v[118:121]
	v_mfma_f32_16x16x32_bf16 v[106:109], v[158:161], v[184:187], v[106:109]
	v_mfma_f32_16x16x32_bf16 v[106:109], v[162:165], v[188:191], v[106:109]
	v_mfma_f32_16x16x32_bf16 v[122:125], v[166:169], v[184:187], v[122:125]
	v_mfma_f32_16x16x32_bf16 v[122:125], v[172:175], v[188:191], v[122:125]
	v_mfma_f32_16x16x32_bf16 v[110:113], v[158:161], v[196:199], v[110:113]
	v_mfma_f32_16x16x32_bf16 v[110:113], v[162:165], v[200:203], v[110:113]
	v_mfma_f32_16x16x32_bf16 v[126:129], v[166:169], v[196:199], v[126:129]
	v_mfma_f32_16x16x32_bf16 v[126:129], v[172:175], v[200:203], v[126:129]
	v_mfma_f32_16x16x32_bf16 v[114:117], v[158:161], v[204:207], v[114:117]
	v_mfma_f32_16x16x32_bf16 v[114:117], v[162:165], v[208:211], v[114:117]
	v_mfma_f32_16x16x32_bf16 v[130:133], v[166:169], v[204:207], v[130:133]
	v_mfma_f32_16x16x32_bf16 v[130:133], v[172:175], v[208:211], v[130:133]
	s_barrier
	s_setprio 0
	ds_read_b128 v[176:179], v136 offset:16384
	ds_read_b128 v[180:183], v136 offset:17408
	ds_read_b128 v[184:187], v136 offset:18432
	ds_read_b128 v[188:191], v136 offset:19456
	ds_read_b128 v[196:199], v136 offset:20480
	ds_read_b128 v[200:203], v136 offset:21504
	ds_read_b128 v[204:207], v136 offset:22528
	ds_read_b128 v[208:211], v136 offset:23552
	s_add_i32 m0, s43, 0x10000
	s_nop 0
	global_load_lds_dwordx4 v134, s[92:93]
	s_nop 0
	s_add_i32 m0, s43, 0x12000
	s_nop 0
	global_load_lds_dwordx4 v135, s[92:93]
	s_add_u32 s92, s92, s16
	s_addc_u32 s93, s93, 0
	s_add_i32 m0, s43, 0x14000
	s_nop 0
	global_load_lds_dwordx4 v134, s[92:93]
	s_nop 0
	s_add_i32 m0, s43, 0x16000
	s_nop 0
	global_load_lds_dwordx4 v135, s[92:93]
	s_nop 0
	s_add_i32 m0, s43, 0
	s_nop 0
	global_load_lds_dwordx4 v134, s[94:95]
	s_nop 0
	s_add_i32 m0, s43, 0x2000
	s_nop 0
	global_load_lds_dwordx4 v135, s[94:95]
	s_waitcnt vmcnt(8)
	s_waitcnt lgkmcnt(0)
	s_setprio 1
	s_barrier
	v_mfma_f32_16x16x32_bf16 v[4:7], v[142:145], v[176:179], v[6:9]
	v_mfma_f32_16x16x32_bf16 v[4:7], v[146:149], v[180:183], v[4:7]
	v_mfma_f32_16x16x32_bf16 v[22:25], v[150:153], v[176:179], v[22:25]
	v_mfma_f32_16x16x32_bf16 v[22:25], v[154:157], v[180:183], v[22:25]
	v_mfma_f32_16x16x32_bf16 v[8:11], v[142:145], v[184:187], v[10:13]
	v_mfma_f32_16x16x32_bf16 v[10:13], v[146:149], v[188:191], v[8:11]
	v_mfma_f32_16x16x32_bf16 v[26:29], v[150:153], v[184:187], v[26:29]
	v_mfma_f32_16x16x32_bf16 v[26:29], v[154:157], v[188:191], v[26:29]
	v_mfma_f32_16x16x32_bf16 v[14:17], v[142:145], v[196:199], v[14:17]
	v_mfma_f32_16x16x32_bf16 v[14:17], v[146:149], v[200:203], v[14:17]
	v_mfma_f32_16x16x32_bf16 v[30:33], v[150:153], v[196:199], v[30:33]
	v_mfma_f32_16x16x32_bf16 v[30:33], v[154:157], v[200:203], v[30:33]
	v_mfma_f32_16x16x32_bf16 v[18:21], v[142:145], v[204:207], v[18:21]
	v_mfma_f32_16x16x32_bf16 v[18:21], v[146:149], v[208:211], v[18:21]
	v_mfma_f32_16x16x32_bf16 v[34:37], v[150:153], v[204:207], v[34:37]
	v_mfma_f32_16x16x32_bf16 v[34:37], v[154:157], v[208:211], v[34:37]
	v_mfma_f32_16x16x32_bf16 v[38:41], v[158:161], v[176:179], v[38:41]
	v_mfma_f32_16x16x32_bf16 v[38:41], v[162:165], v[180:183], v[38:41]
	v_mfma_f32_16x16x32_bf16 v[54:57], v[166:169], v[176:179], v[54:57]
	v_mfma_f32_16x16x32_bf16 v[54:57], v[172:175], v[180:183], v[54:57]
	v_mfma_f32_16x16x32_bf16 v[42:45], v[158:161], v[184:187], v[42:45]
	v_mfma_f32_16x16x32_bf16 v[42:45], v[162:165], v[188:191], v[42:45]
	v_mfma_f32_16x16x32_bf16 v[58:61], v[166:169], v[184:187], v[58:61]
	v_mfma_f32_16x16x32_bf16 v[58:61], v[172:175], v[188:191], v[58:61]
	v_mfma_f32_16x16x32_bf16 v[46:49], v[158:161], v[196:199], v[46:49]
	v_mfma_f32_16x16x32_bf16 v[46:49], v[162:165], v[200:203], v[46:49]
	v_mfma_f32_16x16x32_bf16 v[62:65], v[166:169], v[196:199], v[62:65]
	v_mfma_f32_16x16x32_bf16 v[62:65], v[172:175], v[200:203], v[62:65]
	v_mfma_f32_16x16x32_bf16 v[50:53], v[158:161], v[204:207], v[50:53]
	v_mfma_f32_16x16x32_bf16 v[50:53], v[162:165], v[208:211], v[50:53]
	v_mfma_f32_16x16x32_bf16 v[66:69], v[166:169], v[204:207], v[66:69]
	v_mfma_f32_16x16x32_bf16 v[66:69], v[172:175], v[208:211], v[66:69]
	s_barrier
	s_setprio 0
	ds_read_b128 v[142:145], v139
	ds_read_b128 v[146:149], v139 offset:1024
	ds_read_b128 v[150:153], v139 offset:2048
	ds_read_b128 v[154:157], v139 offset:3072
	ds_read_b128 v[158:161], v140
	ds_read_b128 v[162:165], v140 offset:1024
	ds_read_b128 v[166:169], v140 offset:2048
	ds_read_b128 v[172:175], v140 offset:3072
	ds_read_b128 v[176:179], v136 offset:32768
	ds_read_b128 v[180:183], v136 offset:33792
	ds_read_b128 v[184:187], v136 offset:34816
	ds_read_b128 v[188:191], v136 offset:35840
	ds_read_b128 v[196:199], v136 offset:36864
	ds_read_b128 v[200:203], v136 offset:37888
	ds_read_b128 v[204:207], v136 offset:38912
	ds_read_b128 v[208:211], v136 offset:39936
	s_add_u32 s92, s94, s16
	s_addc_u32 s93, s95, 0
	s_add_i32 m0, s43, 0x4000
	s_nop 0
	global_load_lds_dwordx4 v134, s[92:93]
	s_nop 0
	s_add_i32 m0, s43, 0x6000
	s_nop 0
	global_load_lds_dwordx4 v135, s[92:93]
	s_waitcnt vmcnt(8)
	s_waitcnt lgkmcnt(0)
	s_setprio 1
	s_barrier
	v_mfma_f32_16x16x32_bf16 v[70:73], v[142:145], v[176:179], v[70:73]
	v_mfma_f32_16x16x32_bf16 v[70:73], v[146:149], v[180:183], v[70:73]
	v_mfma_f32_16x16x32_bf16 v[86:89], v[150:153], v[176:179], v[86:89]
	v_mfma_f32_16x16x32_bf16 v[86:89], v[154:157], v[180:183], v[86:89]
	v_mfma_f32_16x16x32_bf16 v[74:77], v[142:145], v[184:187], v[74:77]
	v_mfma_f32_16x16x32_bf16 v[74:77], v[146:149], v[188:191], v[74:77]
	v_mfma_f32_16x16x32_bf16 v[90:93], v[150:153], v[184:187], v[90:93]
	v_mfma_f32_16x16x32_bf16 v[90:93], v[154:157], v[188:191], v[90:93]
	v_mfma_f32_16x16x32_bf16 v[78:81], v[142:145], v[196:199], v[78:81]
	v_mfma_f32_16x16x32_bf16 v[78:81], v[146:149], v[200:203], v[78:81]
	v_mfma_f32_16x16x32_bf16 v[94:97], v[150:153], v[196:199], v[94:97]
	v_mfma_f32_16x16x32_bf16 v[94:97], v[154:157], v[200:203], v[94:97]
	v_mfma_f32_16x16x32_bf16 v[82:85], v[142:145], v[204:207], v[82:85]
	v_mfma_f32_16x16x32_bf16 v[82:85], v[146:149], v[208:211], v[82:85]
	v_mfma_f32_16x16x32_bf16 v[98:101], v[150:153], v[204:207], v[98:101]
	v_mfma_f32_16x16x32_bf16 v[98:101], v[154:157], v[208:211], v[98:101]
	v_mfma_f32_16x16x32_bf16 v[102:105], v[158:161], v[176:179], v[102:105]
	v_mfma_f32_16x16x32_bf16 v[102:105], v[162:165], v[180:183], v[102:105]
	v_mfma_f32_16x16x32_bf16 v[118:121], v[166:169], v[176:179], v[118:121]
	v_mfma_f32_16x16x32_bf16 v[118:121], v[172:175], v[180:183], v[118:121]
	v_mfma_f32_16x16x32_bf16 v[106:109], v[158:161], v[184:187], v[106:109]
	v_mfma_f32_16x16x32_bf16 v[106:109], v[162:165], v[188:191], v[106:109]
	v_mfma_f32_16x16x32_bf16 v[122:125], v[166:169], v[184:187], v[122:125]
	v_mfma_f32_16x16x32_bf16 v[122:125], v[172:175], v[188:191], v[122:125]
	v_mfma_f32_16x16x32_bf16 v[110:113], v[158:161], v[196:199], v[110:113]
	v_mfma_f32_16x16x32_bf16 v[110:113], v[162:165], v[200:203], v[110:113]
	v_mfma_f32_16x16x32_bf16 v[126:129], v[166:169], v[196:199], v[126:129]
	v_mfma_f32_16x16x32_bf16 v[126:129], v[172:175], v[200:203], v[126:129]
	v_mfma_f32_16x16x32_bf16 v[114:117], v[158:161], v[204:207], v[114:117]
	v_mfma_f32_16x16x32_bf16 v[114:117], v[162:165], v[208:211], v[114:117]
	v_mfma_f32_16x16x32_bf16 v[130:133], v[166:169], v[204:207], v[130:133]
	v_mfma_f32_16x16x32_bf16 v[130:133], v[172:175], v[208:211], v[130:133]
	s_barrier
	s_setprio 0
	ds_read_b128 v[176:179], v136 offset:49152
	ds_read_b128 v[180:183], v136 offset:50176
	ds_read_b128 v[184:187], v136 offset:51200
	ds_read_b128 v[188:191], v136 offset:52224
	ds_read_b128 v[196:199], v136 offset:53248
	ds_read_b128 v[200:203], v136 offset:54272
	ds_read_b128 v[204:207], v136 offset:55296
	ds_read_b128 v[208:211], v136 offset:56320
	s_add_i32 m0, s43, 0x18000
	s_nop 0
	global_load_lds_dwordx4 v134, s[12:13]
	s_nop 0
	s_add_i32 m0, s43, 0x1a000
	s_nop 0
	global_load_lds_dwordx4 v135, s[12:13]
	s_add_u32 s12, s12, s16
	s_addc_u32 s13, s13, 0
	s_add_i32 m0, s43, 0x1c000
	s_nop 0
	global_load_lds_dwordx4 v134, s[12:13]
	s_nop 0
	s_add_i32 m0, s43, 0x1e000
	s_nop 0
	global_load_lds_dwordx4 v135, s[12:13]
	s_nop 0
	s_add_i32 m0, s43, 0x8000
	s_nop 0
	global_load_lds_dwordx4 v134, s[2:3]
	s_nop 0
	s_add_i32 m0, s43, 0xa000
	s_nop 0
	global_load_lds_dwordx4 v135, s[2:3]
	s_waitcnt vmcnt(8)
	s_waitcnt lgkmcnt(0)
	s_setprio 1
	s_barrier
	v_mfma_f32_16x16x32_bf16 v[4:7], v[142:145], v[176:179], v[4:7]
	v_mfma_f32_16x16x32_bf16 v[6:9], v[146:149], v[180:183], v[4:7]
	v_mfma_f32_16x16x32_bf16 v[22:25], v[150:153], v[176:179], v[22:25]
	v_mfma_f32_16x16x32_bf16 v[22:25], v[154:157], v[180:183], v[22:25]
	v_mfma_f32_16x16x32_bf16 v[10:13], v[142:145], v[184:187], v[10:13]
	v_mfma_f32_16x16x32_bf16 v[10:13], v[146:149], v[188:191], v[10:13]
	v_mfma_f32_16x16x32_bf16 v[26:29], v[150:153], v[184:187], v[26:29]
	v_mfma_f32_16x16x32_bf16 v[26:29], v[154:157], v[188:191], v[26:29]
	v_mfma_f32_16x16x32_bf16 v[14:17], v[142:145], v[196:199], v[14:17]
	v_mfma_f32_16x16x32_bf16 v[14:17], v[146:149], v[200:203], v[14:17]
	v_mfma_f32_16x16x32_bf16 v[30:33], v[150:153], v[196:199], v[30:33]
	v_mfma_f32_16x16x32_bf16 v[30:33], v[154:157], v[200:203], v[30:33]
	v_mfma_f32_16x16x32_bf16 v[18:21], v[142:145], v[204:207], v[18:21]
	v_mfma_f32_16x16x32_bf16 v[18:21], v[146:149], v[208:211], v[18:21]
	v_mfma_f32_16x16x32_bf16 v[34:37], v[150:153], v[204:207], v[34:37]
	v_mfma_f32_16x16x32_bf16 v[34:37], v[154:157], v[208:211], v[34:37]
	v_mfma_f32_16x16x32_bf16 v[38:41], v[158:161], v[176:179], v[38:41]
	v_mfma_f32_16x16x32_bf16 v[38:41], v[162:165], v[180:183], v[38:41]
	v_mfma_f32_16x16x32_bf16 v[54:57], v[166:169], v[176:179], v[54:57]
	v_mfma_f32_16x16x32_bf16 v[54:57], v[172:175], v[180:183], v[54:57]
	v_mfma_f32_16x16x32_bf16 v[42:45], v[158:161], v[184:187], v[42:45]
	v_mfma_f32_16x16x32_bf16 v[42:45], v[162:165], v[188:191], v[42:45]
	v_mfma_f32_16x16x32_bf16 v[58:61], v[166:169], v[184:187], v[58:61]
	v_mfma_f32_16x16x32_bf16 v[58:61], v[172:175], v[188:191], v[58:61]
	v_mfma_f32_16x16x32_bf16 v[46:49], v[158:161], v[196:199], v[46:49]
	v_mfma_f32_16x16x32_bf16 v[46:49], v[162:165], v[200:203], v[46:49]
	v_mfma_f32_16x16x32_bf16 v[62:65], v[166:169], v[196:199], v[62:65]
	v_mfma_f32_16x16x32_bf16 v[62:65], v[172:175], v[200:203], v[62:65]
	v_mfma_f32_16x16x32_bf16 v[50:53], v[158:161], v[204:207], v[50:53]
	v_mfma_f32_16x16x32_bf16 v[50:53], v[162:165], v[208:211], v[50:53]
	v_mfma_f32_16x16x32_bf16 v[66:69], v[166:169], v[204:207], v[66:69]
	v_mfma_f32_16x16x32_bf16 v[66:69], v[172:175], v[208:211], v[66:69]
	s_barrier
	s_setprio 0
	s_cmp_ge_u32 s90, s55
	s_cbranch_scc1 .LBB0_848

.LBB0_1071:
	s_add_i32 s16, s38, 1
	s_add_i32 s3, s16, s35
	s_mul_i32 s3, s3, s23
	s_add_i32 s3, s3, s22
	s_add_i32 s12, s18, s3
	s_cmp_lt_i32 s12, s2
	s_cselect_b64 s[78:79], -1, 0
	s_cmp_ge_i32 s12, s2
	s_cselect_b64 s[74:75], -1, 0
	s_lshr_b32 s2, s2, 1
	s_cmp_lt_i32 s12, s2
	s_cselect_b32 s2, 0, s2
	s_cselect_b32 s13, 0, 4
	s_sub_i32 s2, s12, s2
	s_and_b32 s3, s3, 3
	s_ashr_i32 s37, s2, 2
	s_or_b32 s2, s3, s13
	s_or_b32 s53, s2, s28
	s_and_b64 s[2:3], s[78:79], exec
	s_cselect_b32 s82, s53, s7
	s_cselect_b32 s2, s37, s6
	s_ashr_i32 s83, s82, 31
	s_lshl_b64 s[6:7], s[82:83], 19
	s_add_u32 s76, s51, s6
	s_addc_u32 s77, s97, s7
	s_ashr_i32 s3, s2, 31
	s_lshl_b64 s[2:3], s[2:3], 19
	s_add_u32 s80, s56, s2
	s_addc_u32 s81, s96, s3
	s_add_u32 s12, s62, 0x100
	s_addc_u32 s13, s63, 0
	v_add_u32_e32 v134, 0x10000, v151
	v_add_u32_e32 v135, 0x14000, v151
	s_add_u32 s2, s62, 0x180
	ds_read_b128 v[4:7], v134
	ds_read_b128 v[8:11], v134 offset:1024
	ds_read_b128 v[12:15], v134 offset:2048
	ds_read_b128 v[16:19], v134 offset:3072
	ds_read_b128 v[20:23], v135
	ds_read_b128 v[24:27], v135 offset:1024
	ds_read_b128 v[28:31], v135 offset:2048
	ds_read_b128 v[32:35], v135 offset:3072
	s_addc_u32 s3, s63, 0
	s_and_b64 s[6:7], s[78:79], exec
	s_cselect_b32 s33, s77, s63
	s_cselect_b32 s39, s76, s62
	s_add_u32 s6, s64, 0x100
	s_addc_u32 s7, s65, 0
	s_and_b64 s[26:27], s[78:79], exec
	s_mov_b32 s29, 2
	s_cselect_b32 s54, s81, s65
	s_cselect_b32 s47, s80, s64
	ds_read_b128 v[36:39], v152
	ds_read_b128 v[40:43], v152 offset:1024
	ds_read_b128 v[44:47], v152 offset:2048
	ds_read_b128 v[48:51], v152 offset:3072
	ds_read_b128 v[52:55], v152 offset:4096
	ds_read_b128 v[56:59], v152 offset:5120
	ds_read_b128 v[60:63], v152 offset:6144
	ds_read_b128 v[64:67], v152 offset:7168
	s_add_u32 s26, s62, 0x40080
	s_addc_u32 s27, s63, 0
	s_add_i32 m0, s69, 0xc000
	s_nop 0
	global_load_lds_dwordx4 v147, s[26:27]
	s_nop 0
	s_add_i32 m0, s69, 0xe000
	s_nop 0
	global_load_lds_dwordx4 v148, s[26:27]
	s_waitcnt vmcnt(8)
	s_waitcnt lgkmcnt(0)
	s_setprio 1
	s_barrier
	v_mfma_f32_16x16x32_bf16 v[92:95], v[4:7], v[60:63], 0
	v_mfma_f32_16x16x32_bf16 v[96:99], v[8:11], v[64:67], v[92:95]
	v_mfma_f32_16x16x32_bf16 v[68:71], v[4:7], v[36:39], 0
	v_mfma_f32_16x16x32_bf16 v[68:71], v[8:11], v[40:43], v[68:71]
	v_mfma_f32_16x16x32_bf16 v[72:75], v[12:15], v[36:39], 0
	v_mfma_f32_16x16x32_bf16 v[72:75], v[16:19], v[40:43], v[72:75]
	v_mfma_f32_16x16x32_bf16 v[76:79], v[4:7], v[44:47], 0
	v_mfma_f32_16x16x32_bf16 v[76:79], v[8:11], v[48:51], v[76:79]
	v_mfma_f32_16x16x32_bf16 v[80:83], v[12:15], v[44:47], 0
	v_mfma_f32_16x16x32_bf16 v[80:83], v[16:19], v[48:51], v[80:83]
	v_mfma_f32_16x16x32_bf16 v[84:87], v[4:7], v[52:55], 0
	v_mfma_f32_16x16x32_bf16 v[84:87], v[8:11], v[56:59], v[84:87]
	v_mfma_f32_16x16x32_bf16 v[88:91], v[12:15], v[52:55], 0
	v_mfma_f32_16x16x32_bf16 v[88:91], v[16:19], v[56:59], v[88:91]
	v_mfma_f32_16x16x32_bf16 v[92:95], v[12:15], v[60:63], 0
	v_mfma_f32_16x16x32_bf16 v[104:107], v[16:19], v[64:67], v[92:95]
	v_mfma_f32_16x16x32_bf16 v[92:95], v[20:23], v[36:39], 0
	v_mfma_f32_16x16x32_bf16 v[112:115], v[24:27], v[40:43], v[92:95]
	v_mfma_f32_16x16x32_bf16 v[36:39], v[28:31], v[36:39], 0
	v_mfma_f32_16x16x32_bf16 v[36:39], v[32:35], v[40:43], v[36:39]
	v_mfma_f32_16x16x32_bf16 v[40:43], v[20:23], v[44:47], 0
	v_mfma_f32_16x16x32_bf16 v[40:43], v[24:27], v[48:51], v[40:43]
	v_mfma_f32_16x16x32_bf16 v[44:47], v[28:31], v[44:47], 0
	v_mfma_f32_16x16x32_bf16 v[44:47], v[32:35], v[48:51], v[44:47]
	v_mfma_f32_16x16x32_bf16 v[48:51], v[20:23], v[52:55], 0
	v_mfma_f32_16x16x32_bf16 v[48:51], v[24:27], v[56:59], v[48:51]
	v_mfma_f32_16x16x32_bf16 v[52:55], v[28:31], v[52:55], 0
	v_mfma_f32_16x16x32_bf16 v[52:55], v[32:35], v[56:59], v[52:55]
	v_mfma_f32_16x16x32_bf16 v[56:59], v[20:23], v[60:63], 0
	v_mfma_f32_16x16x32_bf16 v[56:59], v[24:27], v[64:67], v[56:59]
	v_mfma_f32_16x16x32_bf16 v[60:63], v[28:31], v[60:63], 0
	v_mfma_f32_16x16x32_bf16 v[60:63], v[32:35], v[64:67], v[60:63]
	s_barrier
	s_setprio 0
	ds_read_b128 v[64:67], v152 offset:16384
	ds_read_b128 v[92:95], v152 offset:17408
	ds_read_b128 v[100:103], v152 offset:18432
	ds_read_b128 v[108:111], v152 offset:19456
	ds_read_b128 v[116:119], v152 offset:20480
	ds_read_b128 v[120:123], v152 offset:21504
	ds_read_b128 v[124:127], v152 offset:22528
	ds_read_b128 v[128:131], v152 offset:23552
	s_add_i32 m0, s69, 0x10000
	s_nop 0
	global_load_lds_dwordx4 v1, s[6:7]
	s_nop 0
	s_add_i32 m0, s69, 0x12000
	s_nop 0
	global_load_lds_dwordx4 v146, s[6:7]
	s_add_u32 s6, s64, 0x40100
	s_addc_u32 s7, s65, 0
	s_add_i32 m0, s69, 0x14000
	s_nop 0
	global_load_lds_dwordx4 v1, s[6:7]
	s_nop 0
	s_add_i32 m0, s69, 0x16000
	s_nop 0
	global_load_lds_dwordx4 v146, s[6:7]
	s_nop 0
	s_add_i32 m0, s69, 0
	s_nop 0
	global_load_lds_dwordx4 v147, s[12:13]
	s_nop 0
	s_add_i32 m0, s69, 0x2000
	s_nop 0
	global_load_lds_dwordx4 v148, s[12:13]
	s_waitcnt vmcnt(8)
	s_waitcnt lgkmcnt(0)
	s_setprio 1
	s_barrier
	v_mfma_f32_16x16x32_bf16 v[136:139], v[4:7], v[64:67], 0
	v_mfma_f32_16x16x32_bf16 v[138:141], v[8:11], v[92:95], v[136:139]
	v_mfma_f32_16x16x32_bf16 v[154:157], v[4:7], v[100:103], 0
	v_mfma_f32_16x16x32_bf16 v[154:157], v[8:11], v[108:111], v[154:157]
	v_mfma_f32_16x16x32_bf16 v[162:165], v[4:7], v[116:119], 0
	v_mfma_f32_16x16x32_bf16 v[162:165], v[8:11], v[120:123], v[162:165]
	v_mfma_f32_16x16x32_bf16 v[4:7], v[4:7], v[124:127], 0
	v_mfma_f32_16x16x32_bf16 v[4:7], v[8:11], v[128:131], v[4:7]
	v_mfma_f32_16x16x32_bf16 v[8:11], v[12:15], v[124:127], 0
	v_mfma_f32_16x16x32_bf16 v[8:11], v[16:19], v[128:131], v[8:11]
	v_mfma_f32_16x16x32_bf16 v[142:145], v[12:15], v[64:67], 0
	v_mfma_f32_16x16x32_bf16 v[142:145], v[16:19], v[92:95], v[142:145]
	v_mfma_f32_16x16x32_bf16 v[158:161], v[12:15], v[100:103], 0
	v_mfma_f32_16x16x32_bf16 v[158:161], v[16:19], v[108:111], v[158:161]
	v_mfma_f32_16x16x32_bf16 v[166:169], v[12:15], v[116:119], 0
	v_mfma_f32_16x16x32_bf16 v[166:169], v[16:19], v[120:123], v[166:169]
	v_mfma_f32_16x16x32_bf16 v[12:15], v[20:23], v[64:67], 0
	v_mfma_f32_16x16x32_bf16 v[16:19], v[24:27], v[92:95], v[12:15]
	v_mfma_f32_16x16x32_bf16 v[12:15], v[28:31], v[64:67], 0
	v_mfma_f32_16x16x32_bf16 v[172:175], v[32:35], v[92:95], v[12:15]
	v_mfma_f32_16x16x32_bf16 v[12:15], v[20:23], v[100:103], 0
	v_mfma_f32_16x16x32_bf16 v[176:179], v[24:27], v[108:111], v[12:15]
	v_mfma_f32_16x16x32_bf16 v[12:15], v[28:31], v[100:103], 0
	v_mfma_f32_16x16x32_bf16 v[180:183], v[32:35], v[108:111], v[12:15]
	v_mfma_f32_16x16x32_bf16 v[12:15], v[20:23], v[116:119], 0
	v_mfma_f32_16x16x32_bf16 v[184:187], v[24:27], v[120:123], v[12:15]
	v_mfma_f32_16x16x32_bf16 v[12:15], v[28:31], v[116:119], 0
	v_mfma_f32_16x16x32_bf16 v[204:207], v[32:35], v[120:123], v[12:15]
	v_mfma_f32_16x16x32_bf16 v[12:15], v[20:23], v[124:127], 0
	v_mfma_f32_16x16x32_bf16 v[208:211], v[24:27], v[128:131], v[12:15]
	v_mfma_f32_16x16x32_bf16 v[12:15], v[28:31], v[124:127], 0
	v_mfma_f32_16x16x32_bf16 v[212:215], v[32:35], v[128:131], v[12:15]
	s_barrier
	s_setprio 0
	v_add_u32_e32 v136, 0x18000, v151
	v_add_u32_e32 v137, 0x1c000, v151
	s_nop 2
	ds_read_b128 v[12:15], v136
	ds_read_b128 v[24:27], v136 offset:1024
	ds_read_b128 v[32:35], v136 offset:2048
	ds_read_b128 v[216:219], v136 offset:3072
	ds_read_b128 v[220:223], v137
	ds_read_b128 v[224:227], v137 offset:1024
	ds_read_b128 v[228:231], v137 offset:2048
	ds_read_b128 v[232:235], v137 offset:3072
	ds_read_b128 v[20:23], v152 offset:32768
	ds_read_b128 v[28:31], v152 offset:33792
	ds_read_b128 v[236:239], v152 offset:34816
	ds_read_b128 v[240:243], v152 offset:35840
	ds_read_b128 v[244:247], v152 offset:36864
	ds_read_b128 v[248:251], v152 offset:37888
	ds_read_b128 v[200:203], v152 offset:38912
	ds_read_b128 v[196:199], v152 offset:39936
	s_add_u32 s6, s62, 0x40100
	s_addc_u32 s7, s63, 0
	s_add_i32 m0, s69, 0x4000
	s_nop 0
	global_load_lds_dwordx4 v147, s[6:7]
	s_nop 0
	s_add_i32 m0, s69, 0x6000
	s_nop 0
	global_load_lds_dwordx4 v148, s[6:7]
	s_waitcnt vmcnt(8)
	s_waitcnt lgkmcnt(0)
	s_setprio 1
	s_barrier
	v_mfma_f32_16x16x32_bf16 v[64:67], v[12:15], v[20:23], v[68:71]
	v_mfma_f32_16x16x32_bf16 v[124:127], v[24:27], v[28:31], v[64:67]
	v_mfma_f32_16x16x32_bf16 v[64:67], v[32:35], v[20:23], v[72:75]
	v_mfma_f32_16x16x32_bf16 v[116:119], v[216:219], v[28:31], v[64:67]
	v_mfma_f32_16x16x32_bf16 v[64:67], v[12:15], v[236:239], v[76:79]
	v_mfma_f32_16x16x32_bf16 v[108:111], v[24:27], v[240:243], v[64:67]
	v_mfma_f32_16x16x32_bf16 v[64:67], v[32:35], v[236:239], v[80:83]
	v_mfma_f32_16x16x32_bf16 v[100:103], v[216:219], v[240:243], v[64:67]
	v_mfma_f32_16x16x32_bf16 v[64:67], v[12:15], v[244:247], v[84:87]
	v_mfma_f32_16x16x32_bf16 v[92:95], v[24:27], v[248:251], v[64:67]
	v_mfma_f32_16x16x32_bf16 v[64:67], v[32:35], v[244:247], v[88:91]
	v_mfma_f32_16x16x32_bf16 v[84:87], v[216:219], v[248:251], v[64:67]
	v_mfma_f32_16x16x32_bf16 v[64:67], v[12:15], v[200:203], v[96:99]
	v_mfma_f32_16x16x32_bf16 v[76:79], v[24:27], v[196:199], v[64:67]
	v_mfma_f32_16x16x32_bf16 v[64:67], v[32:35], v[200:203], v[104:107]
	v_mfma_f32_16x16x32_bf16 v[64:67], v[216:219], v[196:199], v[64:67]
	v_mfma_f32_16x16x32_bf16 v[68:71], v[220:223], v[20:23], v[112:115]
	v_mfma_f32_16x16x32_bf16 v[128:131], v[224:227], v[28:31], v[68:71]
	v_mfma_f32_16x16x32_bf16 v[20:23], v[228:231], v[20:23], v[36:39]
	v_mfma_f32_16x16x32_bf16 v[120:123], v[232:235], v[28:31], v[20:23]
	v_mfma_f32_16x16x32_bf16 v[20:23], v[220:223], v[236:239], v[40:43]
	v_mfma_f32_16x16x32_bf16 v[112:115], v[224:227], v[240:243], v[20:23]
	v_mfma_f32_16x16x32_bf16 v[20:23], v[228:231], v[236:239], v[44:47]
	v_mfma_f32_16x16x32_bf16 v[104:107], v[232:235], v[240:243], v[20:23]
	v_mfma_f32_16x16x32_bf16 v[20:23], v[220:223], v[244:247], v[48:51]
	v_mfma_f32_16x16x32_bf16 v[96:99], v[224:227], v[248:251], v[20:23]
	v_mfma_f32_16x16x32_bf16 v[20:23], v[228:231], v[244:247], v[52:55]
	v_mfma_f32_16x16x32_bf16 v[88:91], v[232:235], v[248:251], v[20:23]
	v_mfma_f32_16x16x32_bf16 v[20:23], v[220:223], v[200:203], v[56:59]
	v_mfma_f32_16x16x32_bf16 v[80:83], v[224:227], v[196:199], v[20:23]
	v_mfma_f32_16x16x32_bf16 v[20:23], v[228:231], v[200:203], v[60:63]
	v_mfma_f32_16x16x32_bf16 v[72:75], v[232:235], v[196:199], v[20:23]
	s_barrier
	s_setprio 0
	s_add_u32 s6, s64, 0x180
	ds_read_b128 v[40:43], v152 offset:49152
	ds_read_b128 v[48:51], v152 offset:50176
	ds_read_b128 v[196:199], v152 offset:51200
	ds_read_b128 v[200:203], v152 offset:52224
	ds_read_b128 v[236:239], v152 offset:53248
	ds_read_b128 v[240:243], v152 offset:54272
	ds_read_b128 v[244:247], v152 offset:55296
	ds_read_b128 v[248:251], v152 offset:56320
	s_addc_u32 s7, s65, 0
	s_add_i32 m0, s69, 0x18000
	s_nop 0
	global_load_lds_dwordx4 v1, s[6:7]
	s_nop 0
	s_add_i32 m0, s69, 0x1a000
	s_nop 0
	global_load_lds_dwordx4 v146, s[6:7]
	s_add_u32 s6, s64, 0x40180
	s_addc_u32 s7, s65, 0
	s_add_i32 m0, s69, 0x1c000
	s_nop 0
	global_load_lds_dwordx4 v1, s[6:7]
	s_nop 0
	s_add_i32 m0, s69, 0x1e000
	s_nop 0
	global_load_lds_dwordx4 v146, s[6:7]
	s_nop 0
	s_add_i32 m0, s69, 0x8000
	s_nop 0
	global_load_lds_dwordx4 v147, s[2:3]
	s_nop 0
	s_add_i32 m0, s69, 0xa000
	s_nop 0
	global_load_lds_dwordx4 v148, s[2:3]
	s_waitcnt vmcnt(8)
	s_waitcnt lgkmcnt(0)
	s_setprio 1
	s_barrier
	v_mfma_f32_16x16x32_bf16 v[20:23], v[12:15], v[40:43], v[138:141]
	v_mfma_f32_16x16x32_bf16 v[60:63], v[24:27], v[48:51], v[20:23]
	v_mfma_f32_16x16x32_bf16 v[20:23], v[32:35], v[40:43], v[142:145]
	v_mfma_f32_16x16x32_bf16 v[52:55], v[216:219], v[48:51], v[20:23]
	v_mfma_f32_16x16x32_bf16 v[20:23], v[12:15], v[196:199], v[154:157]
	v_mfma_f32_16x16x32_bf16 v[44:47], v[24:27], v[200:203], v[20:23]
	v_mfma_f32_16x16x32_bf16 v[20:23], v[32:35], v[196:199], v[158:161]
	v_mfma_f32_16x16x32_bf16 v[36:39], v[216:219], v[200:203], v[20:23]
	v_mfma_f32_16x16x32_bf16 v[20:23], v[12:15], v[236:239], v[162:165]
	v_mfma_f32_16x16x32_bf16 v[28:31], v[24:27], v[240:243], v[20:23]
	v_mfma_f32_16x16x32_bf16 v[4:7], v[12:15], v[244:247], v[4:7]
	v_mfma_f32_16x16x32_bf16 v[12:15], v[24:27], v[248:251], v[4:7]
	v_mfma_f32_16x16x32_bf16 v[20:23], v[32:35], v[236:239], v[166:169]
	v_mfma_f32_16x16x32_bf16 v[20:23], v[216:219], v[240:243], v[20:23]
	v_mfma_f32_16x16x32_bf16 v[4:7], v[32:35], v[244:247], v[8:11]
	v_mfma_f32_16x16x32_bf16 v[4:7], v[216:219], v[248:251], v[4:7]
	v_mfma_f32_16x16x32_bf16 v[8:11], v[220:223], v[40:43], v[16:19]
	v_mfma_f32_16x16x32_bf16 v[68:71], v[224:227], v[48:51], v[8:11]
	v_mfma_f32_16x16x32_bf16 v[8:11], v[228:231], v[40:43], v[172:175]
	v_mfma_f32_16x16x32_bf16 v[56:59], v[232:235], v[48:51], v[8:11]
	v_mfma_f32_16x16x32_bf16 v[8:11], v[220:223], v[196:199], v[176:179]
	v_mfma_f32_16x16x32_bf16 v[48:51], v[224:227], v[200:203], v[8:11]
	v_mfma_f32_16x16x32_bf16 v[8:11], v[228:231], v[196:199], v[180:183]
	v_mfma_f32_16x16x32_bf16 v[40:43], v[232:235], v[200:203], v[8:11]
	v_mfma_f32_16x16x32_bf16 v[8:11], v[220:223], v[236:239], v[184:187]
	v_mfma_f32_16x16x32_bf16 v[32:35], v[224:227], v[240:243], v[8:11]
	v_mfma_f32_16x16x32_bf16 v[8:11], v[228:231], v[236:239], v[204:207]
	v_mfma_f32_16x16x32_bf16 v[24:27], v[232:235], v[240:243], v[8:11]
	v_mfma_f32_16x16x32_bf16 v[8:11], v[220:223], v[244:247], v[208:211]
	v_mfma_f32_16x16x32_bf16 v[16:19], v[224:227], v[248:251], v[8:11]
	v_mfma_f32_16x16x32_bf16 v[8:11], v[228:231], v[244:247], v[212:215]
	v_mfma_f32_16x16x32_bf16 v[8:11], v[232:235], v[248:251], v[8:11]
	s_barrier
	s_setprio 0
	s_add_i32 s2, s82, 1
	s_lshl_b32 s58, s82, 6
	s_and_b32 s3, s2, 31
	s_lshl_b32 s2, s2, 6
	s_add_i32 s59, s58, 0x9000
	s_add_i32 s52, s58, 0x8000
	s_add_i32 s40, s58, 0x7000
	s_addk_i32 s2, 0x6000
	s_cmp_eq_u32 s3, 0
	s_cselect_b32 s41, 0, 32
	s_cselect_b32 s50, 0, s2
	s_add_i32 s18, s58, 0x6000
	s_add_i32 s26, s58, 0x5000
	s_and_b32 s2, s82, 31
	s_add_i32 s3, s58, 0x4fc0
	s_cmp_eq_u32 s2, 0
	s_cselect_b32 s27, 0, 0x48
	s_cselect_b32 s6, 0, s3
	s_add_i32 s7, s58, 0x4000
	s_addk_i32 s58, 0x3000
	s_lshl_b64 s[2:3], s[82:83], 14
	s_add_u32 s84, s20, s2
	s_addc_u32 s85, s36, s3
	s_lshl_b32 s2, s82, 8
	s_and_b32 s2, s2, 0x400
	s_add_i32 s83, s2, 0
	s_add_i32 s83, s83, 0x24400
